# plus: k_rope tile epilogue (phase 8): cos/sin loads hoisted above the two preceding stores, counted vmcnt
# speedup vs baseline: 1.0036x; 1.0026x over previous
;   DI float* rope() const { return (float*)(ws + OFF_ROPE); }
;   DI bf16_t* kr() const { return (bf16_t*)(ws + OFF_KR); }
; DI void store_bf4(bf16_t* dst, float a, float b, float c, float d) { u32x2 w; w.x = pk_bf16(a, b); w.y = pk_bf16(c, d); *(u32x2*)dst = w; }
;   DI void operator()(const f32x16 (&acc)[2][4], int mbase, int nbase, int l32, int g) const {
;     if (nbase != 6400) return;
; #pragma unroll
;     for (int mb = 0; mb < 4; ++mb) {
;       const size_t tok = mbase + 32 * mb + l32;
;       const int pos = (int)(tok & 4095);
; #pragma unroll
;       for (int j = 0; j < 4; ++j) {
;         const int i0 = 8 * j + 4 * g;
;         float o1[4], o2[4];
; #pragma unroll
;         for (int i = 0; i < 4; ++i) {
;           const f32x2 cs = *(const f32x2*)(p->rope() + ((size_t)pos * 32 + i0 + i) * 2);
;           const float x1 = acc[0][mb][4 * j + i], x2 = acc[1][mb][4 * j + i];
;           o1[i] = x1 * cs[0] - x2 * cs[1]; o2[i] = x1 * cs[1] + x2 * cs[0];
;         }
;         store_bf4(p->kr() + tok * 64 + i0, o1[0], o1[1], o1[2], o1[3]);
;         store_bf4(p->kr() + tok * 64 + 32 + i0, o2[0], o2[1], o2[2], o2[3]);
;       }
;     }
.LBB0_911:
	s_cmpk_lg_i32 s38, 0x1900
	s_cbranch_scc1 .LBB0_876
	v_or_b32_e32 v128, s57, v203
	v_lshlrev_b32_e32 v129, 5, v128
	v_lshlrev_b32_e32 v131, 2, v202
	v_and_b32_e32 v150, 0x1f3e0, v129
	v_or_b32_e32 v129, v150, v131
	v_lshlrev_b32_e32 v129, 3, v129
	global_load_dwordx4 v[132:135], v129, s[8:9]
	global_load_dwordx4 v[136:139], v129, s[8:9] offset:16
	v_ashrrev_i32_e32 v129, 31, v128
	v_lshlrev_b64 v[140:141], 7, v[128:129]
	v_lshlrev_b32_e32 v192, 3, v202
	v_or_b32_e32 v130, 8, v131
	v_lshl_add_u64 v[142:143], s[10:11], 0, v[140:141]
	v_lshl_add_u64 v[140:141], s[22:23], 0, v[140:141]
	v_or_b32_e32 v129, v150, v130
	v_lshl_add_u64 v[142:143], v[142:143], 0, v[192:193]
	v_lshl_add_u64 v[140:141], v[140:141], 0, s[28:29]
	v_lshlrev_b32_e32 v129, 3, v129
	v_lshl_add_u64 v[144:145], v[140:141], 0, v[192:193]
	s_waitcnt vmcnt(1)
	v_mov_b32_e32 v146, v132
	v_mov_b32_e32 v147, v134
	v_mov_b32_e32 v134, v133
	s_waitcnt vmcnt(0)
	v_mov_b32_e32 v133, v138
	v_mov_b32_e32 v138, v137
	v_mov_b32_e32 v132, v136
	v_pk_mul_f32 v[136:137], v[112:113], v[134:135]
	v_pk_mul_f32 v[112:113], v[112:113], v[146:147]
	v_pk_mul_f32 v[148:149], v[114:115], v[138:139]
	v_pk_mul_f32 v[114:115], v[114:115], v[132:133]
	v_pk_fma_f32 v[136:137], v[96:97], v[146:147], v[136:137] neg_lo:[0,0,1] neg_hi:[0,0,1]
	v_pk_fma_f32 v[96:97], v[96:97], v[134:135], v[112:113]
	v_pk_fma_f32 v[112:113], v[98:99], v[132:133], v[148:149] neg_lo:[0,0,1] neg_hi:[0,0,1]
	v_pk_fma_f32 v[98:99], v[98:99], v[138:139], v[114:115]
	v_cvt_pk_bf16_f32 v114, v136, v137
	v_cvt_pk_bf16_f32 v115, v112, v113
	v_cvt_pk_bf16_f32 v96, v96, v97
	v_cvt_pk_bf16_f32 v97, v98, v99
	global_load_dwordx4 v[234:237], v129, s[8:9]
	global_load_dwordx4 v[238:241], v129, s[8:9] offset:16
	global_store_dwordx2 v[142:143], v[114:115], off
	global_store_dwordx2 v[144:145], v[96:97], off
	v_or_b32_e32 v112, 16, v131
	v_mov_b32_e32 v97, v193
	v_lshlrev_b32_e32 v96, 1, v130
	v_or_b32_e32 v98, v150, v112
	v_lshlrev_b32_e32 v113, 3, v98
	v_lshl_add_u64 v[98:99], v[140:141], 0, v[96:97]
	s_waitcnt vmcnt(3)
	v_mov_b32_e32 v132, v234
	v_mov_b32_e32 v133, v235
	v_mov_b32_e32 v134, v236
	v_mov_b32_e32 v135, v237
	v_mov_b32_e32 v114, v132
	v_mov_b32_e32 v115, v134
	v_mov_b32_e32 v134, v133
	s_waitcnt vmcnt(2)
	v_mov_b32_e32 v136, v238
	v_mov_b32_e32 v137, v239
	v_mov_b32_e32 v138, v240
	v_mov_b32_e32 v139, v241
	v_mov_b32_e32 v133, v138
	v_mov_b32_e32 v138, v137
	v_mov_b32_e32 v132, v136
	v_pk_mul_f32 v[136:137], v[116:117], v[134:135]
	v_pk_mul_f32 v[116:117], v[116:117], v[114:115]
	v_pk_mul_f32 v[144:145], v[118:119], v[138:139]
	v_pk_mul_f32 v[118:119], v[118:119], v[132:133]
	v_pk_fma_f32 v[114:115], v[100:101], v[114:115], v[136:137] neg_lo:[0,0,1] neg_hi:[0,0,1]
	v_pk_fma_f32 v[100:101], v[100:101], v[134:135], v[116:117]
	v_pk_fma_f32 v[116:117], v[102:103], v[132:133], v[144:145] neg_lo:[0,0,1] neg_hi:[0,0,1]
	v_pk_fma_f32 v[102:103], v[102:103], v[138:139], v[118:119]
	v_cvt_pk_bf16_f32 v114, v114, v115
	v_cvt_pk_bf16_f32 v115, v116, v117
	v_cvt_pk_bf16_f32 v100, v100, v101
	v_cvt_pk_bf16_f32 v101, v102, v103
	global_load_dwordx4 v[234:237], v113, s[8:9]
	global_load_dwordx4 v[238:241], v113, s[8:9] offset:16
	global_store_dwordx2 v[142:143], v[114:115], off offset:16
	global_store_dwordx2 v[98:99], v[100:101], off
	s_nop 0
	v_or_b32_e32 v102, 24, v131
	v_mov_b32_e32 v99, v193
	v_lshlrev_b32_e32 v98, 1, v112
	v_or_b32_e32 v100, v150, v102
	v_lshlrev_b32_e32 v103, 3, v100
	v_lshl_add_u64 v[100:101], v[140:141], 0, v[98:99]
	s_waitcnt vmcnt(3)
	v_mov_b32_e32 v114, v234
	v_mov_b32_e32 v115, v235
	v_mov_b32_e32 v116, v236
	v_mov_b32_e32 v117, v237
	v_mov_b32_e32 v119, v116
	v_mov_b32_e32 v116, v115
	s_waitcnt vmcnt(2)
	v_mov_b32_e32 v132, v238
	v_mov_b32_e32 v133, v239
	v_mov_b32_e32 v134, v240
	v_mov_b32_e32 v135, v241
	v_mov_b32_e32 v115, v134
	v_mov_b32_e32 v134, v133
	v_mov_b32_e32 v118, v114
	v_mov_b32_e32 v114, v132
	v_pk_mul_f32 v[132:133], v[120:121], v[116:117]
	v_pk_mul_f32 v[136:137], v[122:123], v[134:135]
	v_pk_mul_f32 v[120:121], v[120:121], v[118:119]
	v_pk_mul_f32 v[122:123], v[122:123], v[114:115]
	v_pk_fma_f32 v[118:119], v[104:105], v[118:119], v[132:133] neg_lo:[0,0,1] neg_hi:[0,0,1]
	v_pk_fma_f32 v[114:115], v[106:107], v[114:115], v[136:137] neg_lo:[0,0,1] neg_hi:[0,0,1]
	v_pk_fma_f32 v[104:105], v[104:105], v[116:117], v[120:121]
	v_pk_fma_f32 v[106:107], v[106:107], v[134:135], v[122:123]
	v_cvt_pk_bf16_f32 v116, v118, v119
	v_cvt_pk_bf16_f32 v117, v114, v115
	v_cvt_pk_bf16_f32 v104, v104, v105
	v_cvt_pk_bf16_f32 v105, v106, v107
	global_load_dwordx4 v[234:237], v103, s[8:9]
	global_load_dwordx4 v[238:241], v103, s[8:9] offset:16
	global_store_dwordx2 v[142:143], v[116:117], off offset:32
	global_store_dwordx2 v[100:101], v[104:105], off
	s_nop 0
	v_or_b32_e32 v118, 32, v128
	v_lshlrev_b32_e32 v103, 5, v118
	v_and_b32_e32 v103, 0x1f7e0, v103
	v_mov_b32_e32 v101, v193
	v_lshlrev_b32_e32 v100, 1, v102
	v_or_b32_e32 v113, v103, v131
	v_lshl_add_u64 v[120:121], v[140:141], 0, v[100:101]
	v_lshlrev_b32_e32 v113, 3, v113
	v_ashrrev_i32_e32 v119, 31, v118
	s_waitcnt vmcnt(3)
	v_mov_b32_e32 v104, v234
	v_mov_b32_e32 v105, v235
	v_mov_b32_e32 v106, v236
	v_mov_b32_e32 v107, v237
	v_mov_b32_e32 v123, v106
	v_mov_b32_e32 v106, v105
	s_waitcnt vmcnt(2)
;   DI float* rope() const { return (float*)(ws + OFF_ROPE); }
;   DI bf16_t* kr() const { return (bf16_t*)(ws + OFF_KR); }
; DI void store_bf4(bf16_t* dst, float a, float b, float c, float d) { u32x2 w; w.x = pk_bf16(a, b); w.y = pk_bf16(c, d); *(u32x2*)dst = w; }
;   DI void operator()(const f32x16 (&acc)[2][4], int mbase, int nbase, int l32, int g) const {
;     ...
;     for (int mb = 0; mb < 4; ++mb) {
;       const size_t tok = mbase + 32 * mb + l32;
;       const int pos = (int)(tok & 4095);
; #pragma unroll
;       for (int j = 0; j < 4; ++j) {
;         const int i0 = 8 * j + 4 * g;
;         float o1[4], o2[4];
; #pragma unroll
;         for (int i = 0; i < 4; ++i) {
;           const f32x2 cs = *(const f32x2*)(p->rope() + ((size_t)pos * 32 + i0 + i) * 2);
;           const float x1 = acc[0][mb][4 * j + i], x2 = acc[1][mb][4 * j + i];
;           o1[i] = x1 * cs[0] - x2 * cs[1]; o2[i] = x1 * cs[1] + x2 * cs[0];
;         }
;         store_bf4(p->kr() + tok * 64 + i0, o1[0], o1[1], o1[2], o1[3]);
;         store_bf4(p->kr() + tok * 64 + 32 + i0, o2[0], o2[1], o2[2], o2[3]);
;       }
;     }
	v_mov_b32_e32 v114, v238
	v_mov_b32_e32 v115, v239
	v_mov_b32_e32 v116, v240
	v_mov_b32_e32 v117, v241
	v_mov_b32_e32 v105, v116
	v_mov_b32_e32 v116, v115
	v_mov_b32_e32 v122, v104
	v_mov_b32_e32 v104, v114
	v_pk_mul_f32 v[114:115], v[124:125], v[106:107]
	v_pk_mul_f32 v[132:133], v[126:127], v[116:117]
	v_pk_mul_f32 v[124:125], v[124:125], v[122:123]
	v_pk_mul_f32 v[126:127], v[126:127], v[104:105]
	v_pk_fma_f32 v[114:115], v[108:109], v[122:123], v[114:115] neg_lo:[0,0,1] neg_hi:[0,0,1]
	v_pk_fma_f32 v[104:105], v[110:111], v[104:105], v[132:133] neg_lo:[0,0,1] neg_hi:[0,0,1]
	v_pk_fma_f32 v[106:107], v[108:109], v[106:107], v[124:125]
	v_pk_fma_f32 v[108:109], v[110:111], v[116:117], v[126:127]
	v_cvt_pk_bf16_f32 v110, v114, v115
	v_cvt_pk_bf16_f32 v111, v104, v105
	v_cvt_pk_bf16_f32 v104, v106, v107
	v_cvt_pk_bf16_f32 v105, v108, v109
	global_load_dwordx4 v[234:237], v113, s[8:9]
	global_load_dwordx4 v[238:241], v113, s[8:9] offset:16
	global_store_dwordx2 v[142:143], v[110:111], off offset:48
	global_store_dwordx2 v[120:121], v[104:105], off
	s_nop 0
	v_lshlrev_b64 v[114:115], 7, v[118:119]
	v_lshl_add_u64 v[116:117], s[10:11], 0, v[114:115]
	v_lshl_add_u64 v[114:115], s[22:23], 0, v[114:115]
	v_or_b32_e32 v113, v103, v130
	v_lshl_add_u64 v[116:117], v[116:117], 0, v[192:193]
	v_lshl_add_u64 v[114:115], v[114:115], 0, s[28:29]
	v_lshlrev_b32_e32 v113, 3, v113
	v_lshl_add_u64 v[118:119], v[114:115], 0, v[192:193]
	s_waitcnt vmcnt(3)
	v_mov_b32_e32 v104, v234
	v_mov_b32_e32 v105, v235
	v_mov_b32_e32 v106, v236
	v_mov_b32_e32 v107, v237
	v_mov_b32_e32 v120, v104
	v_mov_b32_e32 v121, v106
	v_mov_b32_e32 v106, v105
	s_waitcnt vmcnt(2)
	v_mov_b32_e32 v108, v238
	v_mov_b32_e32 v109, v239
	v_mov_b32_e32 v110, v240
	v_mov_b32_e32 v111, v241
	v_mov_b32_e32 v105, v110
	v_mov_b32_e32 v110, v109
	v_mov_b32_e32 v104, v108
	v_pk_mul_f32 v[108:109], v[80:81], v[106:107]
	v_pk_mul_f32 v[80:81], v[80:81], v[120:121]
	v_pk_mul_f32 v[122:123], v[82:83], v[110:111]
	v_pk_mul_f32 v[82:83], v[82:83], v[104:105]
	v_pk_fma_f32 v[108:109], v[64:65], v[120:121], v[108:109] neg_lo:[0,0,1] neg_hi:[0,0,1]
	v_pk_fma_f32 v[64:65], v[64:65], v[106:107], v[80:81]
	v_pk_fma_f32 v[80:81], v[66:67], v[104:105], v[122:123] neg_lo:[0,0,1] neg_hi:[0,0,1]
	v_pk_fma_f32 v[66:67], v[66:67], v[110:111], v[82:83]
	v_cvt_pk_bf16_f32 v82, v108, v109
	v_cvt_pk_bf16_f32 v83, v80, v81
	v_cvt_pk_bf16_f32 v64, v64, v65
	v_cvt_pk_bf16_f32 v65, v66, v67
	global_load_dwordx4 v[234:237], v113, s[8:9]
	global_load_dwordx4 v[238:241], v113, s[8:9] offset:16
	global_store_dwordx2 v[116:117], v[82:83], off
	global_store_dwordx2 v[118:119], v[64:65], off
	s_nop 0
	v_or_b32_e32 v104, v103, v112
	v_lshlrev_b32_e32 v110, 3, v104
	v_lshl_add_u64 v[104:105], v[114:115], 0, v[96:97]
	s_waitcnt vmcnt(3)
	v_mov_b32_e32 v64, v234
	v_mov_b32_e32 v65, v235
	v_mov_b32_e32 v66, v236
	v_mov_b32_e32 v67, v237
	v_mov_b32_e32 v107, v66
	v_mov_b32_e32 v66, v65
	s_waitcnt vmcnt(2)
	v_mov_b32_e32 v80, v238
	v_mov_b32_e32 v81, v239
	v_mov_b32_e32 v82, v240
	v_mov_b32_e32 v83, v241
	v_mov_b32_e32 v65, v82
	v_mov_b32_e32 v82, v81
	v_mov_b32_e32 v106, v64
	v_mov_b32_e32 v64, v80
	v_pk_mul_f32 v[80:81], v[84:85], v[66:67]
	v_pk_mul_f32 v[108:109], v[86:87], v[82:83]
	v_pk_mul_f32 v[84:85], v[84:85], v[106:107]
	v_pk_mul_f32 v[86:87], v[86:87], v[64:65]
	v_pk_fma_f32 v[80:81], v[68:69], v[106:107], v[80:81] neg_lo:[0,0,1] neg_hi:[0,0,1]
	v_pk_fma_f32 v[64:65], v[70:71], v[64:65], v[108:109] neg_lo:[0,0,1] neg_hi:[0,0,1]
	v_pk_fma_f32 v[66:67], v[68:69], v[66:67], v[84:85]
	v_pk_fma_f32 v[68:69], v[70:71], v[82:83], v[86:87]
	v_cvt_pk_bf16_f32 v70, v80, v81
	v_cvt_pk_bf16_f32 v71, v64, v65
	v_cvt_pk_bf16_f32 v64, v66, v67
	v_cvt_pk_bf16_f32 v65, v68, v69
	global_load_dwordx4 v[234:237], v110, s[8:9]
	global_load_dwordx4 v[238:241], v110, s[8:9] offset:16
	global_store_dwordx2 v[116:117], v[70:71], off offset:16
	global_store_dwordx2 v[104:105], v[64:65], off
	s_nop 0
	v_or_b32_e32 v80, v103, v102
	v_lshlrev_b32_e32 v103, 3, v80
	v_lshl_add_u64 v[80:81], v[114:115], 0, v[98:99]
	s_waitcnt vmcnt(3)
	v_mov_b32_e32 v64, v234
	v_mov_b32_e32 v65, v235
	v_mov_b32_e32 v66, v236
	v_mov_b32_e32 v67, v237
	v_mov_b32_e32 v83, v66
	v_mov_b32_e32 v66, v65
	s_waitcnt vmcnt(2)
	v_mov_b32_e32 v68, v238
	v_mov_b32_e32 v69, v239
	v_mov_b32_e32 v70, v240
	v_mov_b32_e32 v71, v241
	v_mov_b32_e32 v65, v70
	v_mov_b32_e32 v70, v69
	v_mov_b32_e32 v82, v64
	v_mov_b32_e32 v64, v68
	v_pk_mul_f32 v[68:69], v[88:89], v[66:67]
	v_pk_mul_f32 v[86:87], v[90:91], v[70:71]
	v_pk_mul_f32 v[84:85], v[88:89], v[82:83]
	v_pk_mul_f32 v[88:89], v[90:91], v[64:65]
	v_pk_fma_f32 v[68:69], v[72:73], v[82:83], v[68:69] neg_lo:[0,0,1] neg_hi:[0,0,1]
	v_pk_fma_f32 v[64:65], v[74:75], v[64:65], v[86:87] neg_lo:[0,0,1] neg_hi:[0,0,1]
	v_pk_fma_f32 v[66:67], v[72:73], v[66:67], v[84:85]
	v_pk_fma_f32 v[70:71], v[74:75], v[70:71], v[88:89]
	v_cvt_pk_bf16_f32 v68, v68, v69
	v_cvt_pk_bf16_f32 v69, v64, v65
	v_cvt_pk_bf16_f32 v64, v66, v67
	v_cvt_pk_bf16_f32 v65, v70, v71
	global_load_dwordx4 v[234:237], v103, s[8:9]
	global_load_dwordx4 v[238:241], v103, s[8:9] offset:16
	global_store_dwordx2 v[116:117], v[68:69], off offset:32
	global_store_dwordx2 v[80:81], v[64:65], off
	s_nop 0
	v_or_b32_e32 v72, 64, v128
	v_lshlrev_b32_e32 v73, 5, v72
	v_and_b32_e32 v88, 0x1fbe0, v73
	v_or_b32_e32 v73, v88, v131
	v_lshlrev_b32_e32 v73, 3, v73
	v_lshl_add_u64 v[74:75], v[114:115], 0, v[100:101]
	s_waitcnt vmcnt(3)
	v_mov_b32_e32 v64, v234
	v_mov_b32_e32 v65, v235
	v_mov_b32_e32 v66, v236
	v_mov_b32_e32 v67, v237
	v_mov_b32_e32 v81, v66
	v_mov_b32_e32 v66, v65
	s_waitcnt vmcnt(2)
;   DI float* rope() const { return (float*)(ws + OFF_ROPE); }
;   DI bf16_t* kr() const { return (bf16_t*)(ws + OFF_KR); }
; DI void store_bf4(bf16_t* dst, float a, float b, float c, float d) { u32x2 w; w.x = pk_bf16(a, b); w.y = pk_bf16(c, d); *(u32x2*)dst = w; }
;   DI void operator()(const f32x16 (&acc)[2][4], int mbase, int nbase, int l32, int g) const {
;     ...
;     for (int mb = 0; mb < 4; ++mb) {
;       const size_t tok = mbase + 32 * mb + l32;
;       const int pos = (int)(tok & 4095);
; #pragma unroll
;       for (int j = 0; j < 4; ++j) {
;         const int i0 = 8 * j + 4 * g;
;         float o1[4], o2[4];
; #pragma unroll
;         for (int i = 0; i < 4; ++i) {
;           const f32x2 cs = *(const f32x2*)(p->rope() + ((size_t)pos * 32 + i0 + i) * 2);
;           const float x1 = acc[0][mb][4 * j + i], x2 = acc[1][mb][4 * j + i];
;           o1[i] = x1 * cs[0] - x2 * cs[1]; o2[i] = x1 * cs[1] + x2 * cs[0];
;         }
;         store_bf4(p->kr() + tok * 64 + i0, o1[0], o1[1], o1[2], o1[3]);
;         store_bf4(p->kr() + tok * 64 + 32 + i0, o2[0], o2[1], o2[2], o2[3]);
;       }
;     }
	v_mov_b32_e32 v68, v238
	v_mov_b32_e32 v69, v239
	v_mov_b32_e32 v70, v240
	v_mov_b32_e32 v71, v241
	v_mov_b32_e32 v65, v70
	v_mov_b32_e32 v70, v69
	v_mov_b32_e32 v80, v64
	v_mov_b32_e32 v64, v68
	v_pk_mul_f32 v[68:69], v[92:93], v[66:67]
	v_pk_mul_f32 v[84:85], v[94:95], v[70:71]
	v_pk_mul_f32 v[82:83], v[92:93], v[80:81]
	v_pk_mul_f32 v[86:87], v[94:95], v[64:65]
	v_pk_fma_f32 v[68:69], v[76:77], v[80:81], v[68:69] neg_lo:[0,0,1] neg_hi:[0,0,1]
	v_pk_fma_f32 v[64:65], v[78:79], v[64:65], v[84:85] neg_lo:[0,0,1] neg_hi:[0,0,1]
	v_pk_fma_f32 v[66:67], v[76:77], v[66:67], v[82:83]
	v_pk_fma_f32 v[70:71], v[78:79], v[70:71], v[86:87]
	v_cvt_pk_bf16_f32 v68, v68, v69
	v_cvt_pk_bf16_f32 v69, v64, v65
	v_cvt_pk_bf16_f32 v64, v66, v67
	v_cvt_pk_bf16_f32 v65, v70, v71
	global_load_dwordx4 v[234:237], v73, s[8:9]
	global_load_dwordx4 v[238:241], v73, s[8:9] offset:16
	global_store_dwordx2 v[116:117], v[68:69], off offset:48
	global_store_dwordx2 v[74:75], v[64:65], off
	s_nop 0
	v_ashrrev_i32_e32 v73, 31, v72
	v_lshlrev_b64 v[72:73], 7, v[72:73]
	v_lshl_add_u64 v[74:75], s[10:11], 0, v[72:73]
	v_lshl_add_u64 v[72:73], s[22:23], 0, v[72:73]
	v_or_b32_e32 v76, v88, v130
	v_lshl_add_u64 v[74:75], v[74:75], 0, v[192:193]
	v_lshl_add_u64 v[72:73], v[72:73], 0, s[28:29]
	v_lshlrev_b32_e32 v82, 3, v76
	v_lshl_add_u64 v[76:77], v[72:73], 0, v[192:193]
	s_waitcnt vmcnt(3)
	v_mov_b32_e32 v64, v234
	v_mov_b32_e32 v65, v235
	v_mov_b32_e32 v66, v236
	v_mov_b32_e32 v67, v237
	v_mov_b32_e32 v78, v64
	v_mov_b32_e32 v79, v66
	v_mov_b32_e32 v66, v65
	s_waitcnt vmcnt(2)
	v_mov_b32_e32 v68, v238
	v_mov_b32_e32 v69, v239
	v_mov_b32_e32 v70, v240
	v_mov_b32_e32 v71, v241
	v_mov_b32_e32 v65, v70
	v_mov_b32_e32 v70, v69
	v_mov_b32_e32 v64, v68
	v_pk_mul_f32 v[68:69], v[48:49], v[66:67]
	v_pk_mul_f32 v[48:49], v[48:49], v[78:79]
	v_pk_mul_f32 v[80:81], v[50:51], v[70:71]
	v_pk_mul_f32 v[50:51], v[50:51], v[64:65]
	v_pk_fma_f32 v[68:69], v[32:33], v[78:79], v[68:69] neg_lo:[0,0,1] neg_hi:[0,0,1]
	v_pk_fma_f32 v[32:33], v[32:33], v[66:67], v[48:49]
	v_pk_fma_f32 v[48:49], v[34:35], v[64:65], v[80:81] neg_lo:[0,0,1] neg_hi:[0,0,1]
	v_pk_fma_f32 v[34:35], v[34:35], v[70:71], v[50:51]
	v_cvt_pk_bf16_f32 v50, v68, v69
	v_cvt_pk_bf16_f32 v51, v48, v49
	v_cvt_pk_bf16_f32 v32, v32, v33
	v_cvt_pk_bf16_f32 v33, v34, v35
	global_load_dwordx4 v[234:237], v82, s[8:9]
	global_load_dwordx4 v[238:241], v82, s[8:9] offset:16
	global_store_dwordx2 v[74:75], v[50:51], off
	global_store_dwordx2 v[76:77], v[32:33], off
	s_nop 0
	v_or_b32_e32 v64, v88, v112
	v_lshlrev_b32_e32 v70, 3, v64
	v_lshl_add_u64 v[64:65], v[72:73], 0, v[96:97]
	s_waitcnt vmcnt(3)
	v_mov_b32_e32 v32, v234
	v_mov_b32_e32 v33, v235
	v_mov_b32_e32 v34, v236
	v_mov_b32_e32 v35, v237
	v_mov_b32_e32 v67, v34
	v_mov_b32_e32 v34, v33
	s_waitcnt vmcnt(2)
	v_mov_b32_e32 v48, v238
	v_mov_b32_e32 v49, v239
	v_mov_b32_e32 v50, v240
	v_mov_b32_e32 v51, v241
	v_mov_b32_e32 v33, v50
	v_mov_b32_e32 v50, v49
	v_mov_b32_e32 v66, v32
	v_mov_b32_e32 v32, v48
	v_pk_mul_f32 v[48:49], v[52:53], v[34:35]
	v_pk_mul_f32 v[68:69], v[54:55], v[50:51]
	v_pk_mul_f32 v[52:53], v[52:53], v[66:67]
	v_pk_mul_f32 v[54:55], v[54:55], v[32:33]
	v_pk_fma_f32 v[48:49], v[36:37], v[66:67], v[48:49] neg_lo:[0,0,1] neg_hi:[0,0,1]
	v_pk_fma_f32 v[32:33], v[38:39], v[32:33], v[68:69] neg_lo:[0,0,1] neg_hi:[0,0,1]
	v_pk_fma_f32 v[34:35], v[36:37], v[34:35], v[52:53]
	v_pk_fma_f32 v[36:37], v[38:39], v[50:51], v[54:55]
	v_cvt_pk_bf16_f32 v38, v48, v49
	v_cvt_pk_bf16_f32 v39, v32, v33
	v_cvt_pk_bf16_f32 v32, v34, v35
	v_cvt_pk_bf16_f32 v33, v36, v37
	global_load_dwordx4 v[234:237], v70, s[8:9]
	global_load_dwordx4 v[238:241], v70, s[8:9] offset:16
	global_store_dwordx2 v[74:75], v[38:39], off offset:16
	global_store_dwordx2 v[64:65], v[32:33], off
	s_nop 0
	v_or_b32_e32 v48, v88, v102
	v_lshlrev_b32_e32 v64, 3, v48
	v_lshl_add_u64 v[48:49], v[72:73], 0, v[98:99]
	s_waitcnt vmcnt(3)
	v_mov_b32_e32 v32, v234
	v_mov_b32_e32 v33, v235
	v_mov_b32_e32 v34, v236
	v_mov_b32_e32 v35, v237
	v_mov_b32_e32 v51, v34
	v_mov_b32_e32 v34, v33
	s_waitcnt vmcnt(2)
	v_mov_b32_e32 v36, v238
	v_mov_b32_e32 v37, v239
	v_mov_b32_e32 v38, v240
	v_mov_b32_e32 v39, v241
	v_mov_b32_e32 v33, v38
	v_mov_b32_e32 v38, v37
	v_mov_b32_e32 v50, v32
	v_mov_b32_e32 v32, v36
	v_pk_mul_f32 v[36:37], v[56:57], v[34:35]
	v_pk_mul_f32 v[54:55], v[58:59], v[38:39]
	v_pk_mul_f32 v[52:53], v[56:57], v[50:51]
	v_pk_mul_f32 v[56:57], v[58:59], v[32:33]
	v_pk_fma_f32 v[36:37], v[40:41], v[50:51], v[36:37] neg_lo:[0,0,1] neg_hi:[0,0,1]
	v_pk_fma_f32 v[32:33], v[42:43], v[32:33], v[54:55] neg_lo:[0,0,1] neg_hi:[0,0,1]
	v_pk_fma_f32 v[34:35], v[40:41], v[34:35], v[52:53]
	v_pk_fma_f32 v[38:39], v[42:43], v[38:39], v[56:57]
	v_cvt_pk_bf16_f32 v36, v36, v37
	v_cvt_pk_bf16_f32 v37, v32, v33
	v_cvt_pk_bf16_f32 v32, v34, v35
	v_cvt_pk_bf16_f32 v33, v38, v39
	global_load_dwordx4 v[234:237], v64, s[8:9]
	global_load_dwordx4 v[238:241], v64, s[8:9] offset:16
	global_store_dwordx2 v[74:75], v[36:37], off offset:32
	global_store_dwordx2 v[48:49], v[32:33], off
	s_nop 0
	v_or_b32_e32 v40, 0x60, v128
	v_lshlrev_b32_e32 v41, 5, v40
	v_and_b32_e32 v56, 0x1ffe0, v41
	v_or_b32_e32 v41, v56, v131
	v_lshlrev_b32_e32 v41, 3, v41
	v_lshl_add_u64 v[42:43], v[72:73], 0, v[100:101]
	s_waitcnt vmcnt(3)
	v_mov_b32_e32 v32, v234
	v_mov_b32_e32 v33, v235
	v_mov_b32_e32 v34, v236
	v_mov_b32_e32 v35, v237
	v_mov_b32_e32 v49, v34
	v_mov_b32_e32 v34, v33
	s_waitcnt vmcnt(2)
;   DI float* rope() const { return (float*)(ws + OFF_ROPE); }
;   DI bf16_t* kr() const { return (bf16_t*)(ws + OFF_KR); }
; DI void store_bf4(bf16_t* dst, float a, float b, float c, float d) { u32x2 w; w.x = pk_bf16(a, b); w.y = pk_bf16(c, d); *(u32x2*)dst = w; }
;   DI void operator()(const f32x16 (&acc)[2][4], int mbase, int nbase, int l32, int g) const {
;     ...
;     for (int mb = 0; mb < 4; ++mb) {
;       const size_t tok = mbase + 32 * mb + l32;
;       const int pos = (int)(tok & 4095);
; #pragma unroll
;       for (int j = 0; j < 4; ++j) {
;         const int i0 = 8 * j + 4 * g;
;         float o1[4], o2[4];
; #pragma unroll
;         for (int i = 0; i < 4; ++i) {
;           const f32x2 cs = *(const f32x2*)(p->rope() + ((size_t)pos * 32 + i0 + i) * 2);
;           const float x1 = acc[0][mb][4 * j + i], x2 = acc[1][mb][4 * j + i];
;           o1[i] = x1 * cs[0] - x2 * cs[1]; o2[i] = x1 * cs[1] + x2 * cs[0];
;         }
;         store_bf4(p->kr() + tok * 64 + i0, o1[0], o1[1], o1[2], o1[3]);
;         store_bf4(p->kr() + tok * 64 + 32 + i0, o2[0], o2[1], o2[2], o2[3]);
;       }
;     }
;   }
	v_mov_b32_e32 v36, v238
	v_mov_b32_e32 v37, v239
	v_mov_b32_e32 v38, v240
	v_mov_b32_e32 v39, v241
	v_mov_b32_e32 v33, v38
	v_mov_b32_e32 v38, v37
	v_mov_b32_e32 v48, v32
	v_mov_b32_e32 v32, v36
	v_pk_mul_f32 v[36:37], v[60:61], v[34:35]
	v_pk_mul_f32 v[52:53], v[62:63], v[38:39]
	v_pk_mul_f32 v[50:51], v[60:61], v[48:49]
	v_pk_mul_f32 v[54:55], v[62:63], v[32:33]
	v_pk_fma_f32 v[36:37], v[44:45], v[48:49], v[36:37] neg_lo:[0,0,1] neg_hi:[0,0,1]
	v_pk_fma_f32 v[32:33], v[46:47], v[32:33], v[52:53] neg_lo:[0,0,1] neg_hi:[0,0,1]
	v_pk_fma_f32 v[34:35], v[44:45], v[34:35], v[50:51]
	v_pk_fma_f32 v[38:39], v[46:47], v[38:39], v[54:55]
	v_cvt_pk_bf16_f32 v36, v36, v37
	v_cvt_pk_bf16_f32 v37, v32, v33
	v_cvt_pk_bf16_f32 v32, v34, v35
	v_cvt_pk_bf16_f32 v33, v38, v39
	global_load_dwordx4 v[234:237], v41, s[8:9]
	global_load_dwordx4 v[238:241], v41, s[8:9] offset:16
	global_store_dwordx2 v[74:75], v[36:37], off offset:48
	global_store_dwordx2 v[42:43], v[32:33], off
	s_nop 0
	v_ashrrev_i32_e32 v41, 31, v40
	v_lshlrev_b64 v[40:41], 7, v[40:41]
	v_lshl_add_u64 v[42:43], s[10:11], 0, v[40:41]
	v_lshl_add_u64 v[40:41], s[22:23], 0, v[40:41]
	v_or_b32_e32 v44, v56, v130
	v_lshl_add_u64 v[42:43], v[42:43], 0, v[192:193]
	v_lshl_add_u64 v[40:41], v[40:41], 0, s[28:29]
	v_lshlrev_b32_e32 v50, 3, v44
	v_lshl_add_u64 v[44:45], v[40:41], 0, v[192:193]
	s_waitcnt vmcnt(3)
	v_mov_b32_e32 v32, v234
	v_mov_b32_e32 v33, v235
	v_mov_b32_e32 v34, v236
	v_mov_b32_e32 v35, v237
	v_mov_b32_e32 v46, v32
	v_mov_b32_e32 v47, v34
	v_mov_b32_e32 v34, v33
	s_waitcnt vmcnt(2)
	v_mov_b32_e32 v36, v238
	v_mov_b32_e32 v37, v239
	v_mov_b32_e32 v38, v240
	v_mov_b32_e32 v39, v241
	v_mov_b32_e32 v33, v38
	v_mov_b32_e32 v38, v37
	v_mov_b32_e32 v32, v36
	v_pk_mul_f32 v[36:37], v[16:17], v[34:35]
	v_pk_mul_f32 v[16:17], v[16:17], v[46:47]
	v_pk_mul_f32 v[48:49], v[18:19], v[38:39]
	v_pk_mul_f32 v[18:19], v[18:19], v[32:33]
	v_pk_fma_f32 v[36:37], v[0:1], v[46:47], v[36:37] neg_lo:[0,0,1] neg_hi:[0,0,1]
	v_pk_fma_f32 v[0:1], v[0:1], v[34:35], v[16:17]
	v_pk_fma_f32 v[16:17], v[2:3], v[32:33], v[48:49] neg_lo:[0,0,1] neg_hi:[0,0,1]
	v_pk_fma_f32 v[2:3], v[2:3], v[38:39], v[18:19]
	v_cvt_pk_bf16_f32 v18, v36, v37
	v_cvt_pk_bf16_f32 v19, v16, v17
	v_cvt_pk_bf16_f32 v0, v0, v1
	v_cvt_pk_bf16_f32 v1, v2, v3
	global_load_dwordx4 v[234:237], v50, s[8:9]
	global_load_dwordx4 v[238:241], v50, s[8:9] offset:16
	global_store_dwordx2 v[42:43], v[18:19], off
	global_store_dwordx2 v[44:45], v[0:1], off
	s_nop 0
	v_or_b32_e32 v32, v56, v112
	v_lshlrev_b32_e32 v38, 3, v32
	v_lshl_add_u64 v[32:33], v[40:41], 0, v[96:97]
	s_waitcnt vmcnt(3)
	v_mov_b32_e32 v0, v234
	v_mov_b32_e32 v1, v235
	v_mov_b32_e32 v2, v236
	v_mov_b32_e32 v3, v237
	v_mov_b32_e32 v35, v2
	v_mov_b32_e32 v2, v1
	s_waitcnt vmcnt(2)
	v_mov_b32_e32 v16, v238
	v_mov_b32_e32 v17, v239
	v_mov_b32_e32 v18, v240
	v_mov_b32_e32 v19, v241
	v_mov_b32_e32 v1, v18
	v_mov_b32_e32 v18, v17
	v_mov_b32_e32 v34, v0
	v_mov_b32_e32 v0, v16
	v_pk_mul_f32 v[16:17], v[20:21], v[2:3]
	v_pk_mul_f32 v[36:37], v[22:23], v[18:19]
	v_pk_mul_f32 v[20:21], v[20:21], v[34:35]
	v_pk_mul_f32 v[22:23], v[22:23], v[0:1]
	v_pk_fma_f32 v[16:17], v[4:5], v[34:35], v[16:17] neg_lo:[0,0,1] neg_hi:[0,0,1]
	v_pk_fma_f32 v[0:1], v[6:7], v[0:1], v[36:37] neg_lo:[0,0,1] neg_hi:[0,0,1]
	v_pk_fma_f32 v[2:3], v[4:5], v[2:3], v[20:21]
	v_pk_fma_f32 v[4:5], v[6:7], v[18:19], v[22:23]
	v_cvt_pk_bf16_f32 v6, v16, v17
	v_cvt_pk_bf16_f32 v7, v0, v1
	v_cvt_pk_bf16_f32 v0, v2, v3
	v_cvt_pk_bf16_f32 v1, v4, v5
	global_load_dwordx4 v[234:237], v38, s[8:9]
	global_load_dwordx4 v[238:241], v38, s[8:9] offset:16
	global_store_dwordx2 v[42:43], v[6:7], off offset:16
	global_store_dwordx2 v[32:33], v[0:1], off
	s_nop 0
	v_or_b32_e32 v16, v56, v102
	v_lshlrev_b32_e32 v32, 3, v16
	v_lshl_add_u64 v[16:17], v[40:41], 0, v[98:99]
	s_waitcnt vmcnt(3)
	v_mov_b32_e32 v0, v234
	v_mov_b32_e32 v1, v235
	v_mov_b32_e32 v2, v236
	v_mov_b32_e32 v3, v237
	v_mov_b32_e32 v19, v2
	v_mov_b32_e32 v2, v1
	s_waitcnt vmcnt(2)
	v_mov_b32_e32 v4, v238
	v_mov_b32_e32 v5, v239
	v_mov_b32_e32 v6, v240
	v_mov_b32_e32 v7, v241
	v_mov_b32_e32 v1, v6
	v_mov_b32_e32 v6, v5
	v_mov_b32_e32 v18, v0
	v_mov_b32_e32 v0, v4
	v_pk_mul_f32 v[4:5], v[24:25], v[2:3]
	v_pk_mul_f32 v[22:23], v[26:27], v[6:7]
	v_pk_mul_f32 v[20:21], v[24:25], v[18:19]
	v_pk_mul_f32 v[24:25], v[26:27], v[0:1]
	v_pk_fma_f32 v[4:5], v[8:9], v[18:19], v[4:5] neg_lo:[0,0,1] neg_hi:[0,0,1]
	v_pk_fma_f32 v[0:1], v[10:11], v[0:1], v[22:23] neg_lo:[0,0,1] neg_hi:[0,0,1]
	v_pk_fma_f32 v[2:3], v[8:9], v[2:3], v[20:21]
	v_pk_fma_f32 v[6:7], v[10:11], v[6:7], v[24:25]
	v_cvt_pk_bf16_f32 v4, v4, v5
	v_cvt_pk_bf16_f32 v5, v0, v1
	v_cvt_pk_bf16_f32 v0, v2, v3
	v_cvt_pk_bf16_f32 v1, v6, v7
	global_load_dwordx4 v[234:237], v32, s[8:9]
	global_load_dwordx4 v[238:241], v32, s[8:9] offset:16
	global_store_dwordx2 v[42:43], v[4:5], off offset:32
	global_store_dwordx2 v[16:17], v[0:1], off
	s_nop 0
	v_lshl_add_u64 v[8:9], v[40:41], 0, v[100:101]
	s_waitcnt vmcnt(3)
	v_mov_b32_e32 v0, v234
	v_mov_b32_e32 v1, v235
	v_mov_b32_e32 v2, v236
	v_mov_b32_e32 v3, v237
	v_mov_b32_e32 v11, v2
	v_mov_b32_e32 v2, v1
	s_waitcnt vmcnt(2)
	v_mov_b32_e32 v4, v238
	v_mov_b32_e32 v5, v239
	v_mov_b32_e32 v6, v240
	v_mov_b32_e32 v7, v241
	v_mov_b32_e32 v1, v6
	v_mov_b32_e32 v6, v5
	v_mov_b32_e32 v10, v0
	v_mov_b32_e32 v0, v4
	v_pk_mul_f32 v[4:5], v[28:29], v[2:3]
	v_pk_mul_f32 v[18:19], v[30:31], v[6:7]
	v_pk_mul_f32 v[16:17], v[28:29], v[10:11]
	v_pk_mul_f32 v[20:21], v[30:31], v[0:1]
	v_pk_fma_f32 v[4:5], v[12:13], v[10:11], v[4:5] neg_lo:[0,0,1] neg_hi:[0,0,1]
	v_pk_fma_f32 v[0:1], v[14:15], v[0:1], v[18:19] neg_lo:[0,0,1] neg_hi:[0,0,1]
	v_pk_fma_f32 v[2:3], v[12:13], v[2:3], v[16:17]
	v_pk_fma_f32 v[6:7], v[14:15], v[6:7], v[20:21]
	v_cvt_pk_bf16_f32 v4, v4, v5
	v_cvt_pk_bf16_f32 v5, v0, v1
	v_cvt_pk_bf16_f32 v0, v2, v3
	v_cvt_pk_bf16_f32 v1, v6, v7
	global_store_dwordx2 v[42:43], v[4:5], off offset:48
	global_store_dwordx2 v[8:9], v[0:1], off
	s_branch .LBB0_876
